# NSA QK chains: the four K-fragment LDS reads issued together with counted lgkmcnt waits instead of read-wait-MFMA four times
# baseline (speedup 1.0000x reference)
; #define LAS __attribute__((address_space(3)))
; #define MFMA32(a, b, c) __builtin_amdgcn_mfma_f32_32x32x16_bf16((a), (b), (c), 0, 0, 0)
; DI void nsa_unit(const Params& p, LAS unsigned char* lds, unsigned char* ldsg, int bg, int qt, int tid) {
;     ...
;         for (int tile = 0; tile < ntw; ++tile) {
;             int dbase = t - 31 - 512 * tile - 64 * hi;
;             asm volatile("" : "+v"(dbase));
;             const float b0 = -slope2 * (float)dbase;
;             f32x16 s;
; #pragma unroll
;             for (int i = 0; i < 16; ++i) s[i] = fmaf(slope16, (float)((i & 3) + 8 * (i >> 2)), b0);
; #pragma unroll
;             for (int st = 0; st < 4; ++st) {
;                 const bf16x8 a = *(LAS const bf16x8*)(lds + NSA_KC + (32 * tile + c) * 144 + st * 32 + hi * 16);
;                 s = MFMA32(a, qf[st], s);
;             }
;             if (512 * tile + 496 + 31 > tw0) {
; #pragma unroll
;                 for (int i = 0; i < 16; ++i) if ((dbase - 16 * ((i & 3) + 8 * (i >> 2))) < 0) s[i] = -1e30f;
;             }
.LBB0_724:
	v_mov_b32_e32 v25, v22
	ds_read_b128 v[26:29], v21
	ds_read_b128 v[200:203], v21 offset:32
	ds_read_b128 v[204:207], v21 offset:64
	ds_read_b128 v[208:211], v21 offset:96
	v_cvt_f32_i32_e32 v2, v25
	s_cmp_le_i32 s39, s40
	v_mul_f32_e64 v16, -v152, v2
	v_fma_f32 v3, -v152, v2, v64
	v_mov_b32_e32 v2, v16
	v_pk_fma_f32 v[4:5], v[64:65], s[72:73], v[16:17] op_sel_hi:[1,1,0]
	v_fmac_f32_e32 v2, 0, v64
	v_pk_fma_f32 v[6:7], v[64:65], s[74:75], v[16:17] op_sel_hi:[1,1,0]
	v_pk_fma_f32 v[8:9], v[64:65], s[76:77], v[16:17] op_sel_hi:[1,1,0]
	v_pk_fma_f32 v[10:11], v[64:65], s[70:71], v[16:17] op_sel_hi:[1,1,0]
	v_pk_fma_f32 v[12:13], v[64:65], s[78:79], v[16:17] op_sel_hi:[1,1,0]
	v_pk_fma_f32 v[14:15], v[64:65], s[80:81], v[16:17] op_sel_hi:[1,1,0]
	v_pk_fma_f32 v[16:17], v[64:65], s[82:83], v[16:17] op_sel_hi:[1,1,0]
	s_waitcnt lgkmcnt(3)
	s_nop 0
	v_mfma_f32_32x32x16_bf16 v[2:17], v[26:29], v[128:131], v[2:17]
	s_waitcnt lgkmcnt(2)
	v_mfma_f32_32x32x16_bf16 v[2:17], v[200:203], v[132:135], v[2:17]
	s_waitcnt lgkmcnt(1)
	v_mfma_f32_32x32x16_bf16 v[2:17], v[204:207], v[136:139], v[2:17]
	s_waitcnt lgkmcnt(0)
	v_mfma_f32_32x32x16_bf16 v[2:17], v[208:211], v[140:143], v[2:17]
	s_cbranch_scc1 .LBB0_726
	v_cmp_gt_i32_e64 s[30:31], s43, v25
	v_cmp_gt_i32_e64 s[34:35], s41, v25
	v_cmp_gt_i32_e64 s[28:29], s42, v25
	s_and_b64 s[30:31], s[34:35], s[30:31]
	v_cmp_gt_i32_e64 s[26:27], s1, v25
	s_and_b64 s[28:29], s[30:31], s[28:29]
	v_cmp_gt_i32_e64 s[24:25], s0, v25
	s_and_b64 s[26:27], s[28:29], s[26:27]
	v_cmp_gt_i32_e64 s[22:23], s59, v25
	s_and_b64 s[24:25], s[26:27], s[24:25]
	v_cmp_gt_i32_e64 s[20:21], s58, v25
	s_and_b64 s[22:23], s[24:25], s[22:23]
	v_cmp_gt_i32_e64 s[18:19], s33, v25
	s_and_b64 s[20:21], s[22:23], s[20:21]
	v_cmp_gt_i32_e64 s[16:17], s13, v25
	s_and_b64 s[18:19], s[20:21], s[18:19]
	v_cmp_gt_i32_e64 s[14:15], s97, v25
	s_and_b64 s[16:17], s[18:19], s[16:17]
	v_cmp_gt_i32_e64 s[10:11], s90, v25
	s_and_b64 s[14:15], s[16:17], s[14:15]
	v_cmp_gt_i32_e64 s[8:9], s96, v25
	s_and_b64 s[10:11], s[14:15], s[10:11]
	v_cmp_gt_i32_e64 s[6:7], 48, v25
	s_and_b64 s[8:9], s[10:11], s[8:9]
	v_cmp_gt_i32_e64 s[4:5], 32, v25
	s_and_b64 s[6:7], s[8:9], s[6:7]
	v_cmp_gt_i32_e64 s[2:3], 16, v25
	s_and_b64 s[4:5], s[6:7], s[4:5]
	v_cmp_gt_i32_e32 vcc, 0, v25
	s_and_b64 s[2:3], s[4:5], s[2:3]
	s_and_b64 vcc, s[2:3], vcc
	v_cndmask_b32_e64 v17, v17, v164, s[34:35]
	v_cndmask_b32_e64 v16, v16, v164, s[30:31]
	v_cndmask_b32_e64 v15, v15, v164, s[28:29]
	v_cndmask_b32_e64 v14, v14, v164, s[26:27]
	v_cndmask_b32_e64 v13, v13, v164, s[24:25]
	v_cndmask_b32_e64 v12, v12, v164, s[22:23]
	v_cndmask_b32_e64 v11, v11, v164, s[20:21]
	v_cndmask_b32_e64 v10, v10, v164, s[18:19]
	v_cndmask_b32_e64 v9, v9, v164, s[16:17]
	v_cndmask_b32_e64 v8, v8, v164, s[14:15]
	v_cndmask_b32_e64 v7, v7, v164, s[10:11]
	v_cndmask_b32_e64 v6, v6, v164, s[8:9]
	v_cndmask_b32_e64 v5, v5, v164, s[6:7]
	v_cndmask_b32_e64 v4, v4, v164, s[4:5]
	v_cndmask_b32_e64 v3, v3, v164, s[2:3]
	v_cndmask_b32_e32 v2, v2, v164, vcc

; #define LAS __attribute__((address_space(3)))
; #define MFMA32(a, b, c) __builtin_amdgcn_mfma_f32_32x32x16_bf16((a), (b), (c), 0, 0, 0)
; DI void nsa_unit(const Params& p, LAS unsigned char* lds, unsigned char* ldsg, int bg, int qt, int tid) {
;     ...
;         for (int tile = 0; tile < ntw; ++tile) {
;             int dbase = t - 31 - 512 * tile - 64 * hi;
;             asm volatile("" : "+v"(dbase));
;             const float b0 = -slope2 * (float)dbase;
;             f32x16 s;
; #pragma unroll
;             for (int i = 0; i < 16; ++i) s[i] = fmaf(slope16, (float)((i & 3) + 8 * (i >> 2)), b0);
; #pragma unroll
;             for (int st = 0; st < 4; ++st) {
;                 const bf16x8 a = *(LAS const bf16x8*)(lds + NSA_KC + (32 * tile + c) * 144 + st * 32 + hi * 16);
;                 s = MFMA32(a, qf[st], s);
;             }
;             if (512 * tile + 496 + 31 > tw0) {
; #pragma unroll
;                 for (int i = 0; i < 16; ++i) if ((dbase - 16 * ((i & 3) + 8 * (i >> 2))) < 0) s[i] = -1e30f;
;             }
.LBB0_732:
	v_mov_b32_e32 v10, v8
	v_add_u32_e32 v69, 0, v6
	ds_read_b128 v[12:15], v69
	ds_read_b128 v[200:203], v69 offset:32
	ds_read_b128 v[204:207], v69 offset:64
	ds_read_b128 v[208:211], v69 offset:96
	v_cvt_f32_i32_e32 v11, v10
	s_cmp_le_i32 s46, s40
	v_mul_f32_e64 v62, -v152, v11
	v_mov_b32_e32 v48, v62
	v_fma_f32 v49, -v152, v11, v64
	v_fmac_f32_e32 v48, 0, v64
	v_pk_fma_f32 v[50:51], v[64:65], s[72:73], v[62:63] op_sel_hi:[1,1,0]
	v_pk_fma_f32 v[52:53], v[64:65], s[74:75], v[62:63] op_sel_hi:[1,1,0]
	v_pk_fma_f32 v[54:55], v[64:65], s[76:77], v[62:63] op_sel_hi:[1,1,0]
	v_pk_fma_f32 v[56:57], v[64:65], s[70:71], v[62:63] op_sel_hi:[1,1,0]
	v_pk_fma_f32 v[58:59], v[64:65], s[78:79], v[62:63] op_sel_hi:[1,1,0]
	v_pk_fma_f32 v[60:61], v[64:65], s[80:81], v[62:63] op_sel_hi:[1,1,0]
	v_pk_fma_f32 v[62:63], v[64:65], s[82:83], v[62:63] op_sel_hi:[1,1,0]
	s_waitcnt lgkmcnt(3)
	s_nop 0
	v_mfma_f32_32x32x16_bf16 v[48:63], v[12:15], v[128:131], v[48:63]
	s_waitcnt lgkmcnt(2)
	v_mfma_f32_32x32x16_bf16 v[48:63], v[200:203], v[132:135], v[48:63]
	s_waitcnt lgkmcnt(1)
	v_mfma_f32_32x32x16_bf16 v[48:63], v[204:207], v[136:139], v[48:63]
	s_waitcnt lgkmcnt(0)
	v_mfma_f32_32x32x16_bf16 v[48:63], v[208:211], v[140:143], v[48:63]
	s_cbranch_scc1 .LBB0_734
	v_cmp_gt_i32_e64 s[36:37], s43, v10
	v_cmp_gt_i32_e64 s[38:39], s41, v10
	v_cmp_gt_i32_e64 s[34:35], s42, v10
	s_and_b64 s[36:37], s[38:39], s[36:37]
	v_cmp_gt_i32_e64 s[30:31], s1, v10
	s_and_b64 s[34:35], s[36:37], s[34:35]
	v_cmp_gt_i32_e64 s[28:29], s0, v10
	s_and_b64 s[30:31], s[34:35], s[30:31]
	v_cmp_gt_i32_e64 s[26:27], s59, v10
	s_and_b64 s[28:29], s[30:31], s[28:29]
	v_cmp_gt_i32_e64 s[24:25], s58, v10
	s_and_b64 s[26:27], s[28:29], s[26:27]
	v_cmp_gt_i32_e64 s[22:23], s33, v10
	s_and_b64 s[24:25], s[26:27], s[24:25]
	v_cmp_gt_i32_e64 s[20:21], s13, v10
	s_and_b64 s[22:23], s[24:25], s[22:23]
	v_cmp_gt_i32_e64 s[18:19], s97, v10
	s_and_b64 s[20:21], s[22:23], s[20:21]
	v_cmp_gt_i32_e64 s[16:17], s90, v10
	s_and_b64 s[18:19], s[20:21], s[18:19]
	v_cmp_gt_i32_e64 s[14:15], s96, v10
	s_and_b64 s[16:17], s[18:19], s[16:17]
	v_cmp_gt_i32_e64 s[10:11], 48, v10
	s_and_b64 s[14:15], s[16:17], s[14:15]
	v_cmp_gt_i32_e64 s[8:9], 32, v10
	s_and_b64 s[10:11], s[14:15], s[10:11]
	v_cmp_gt_i32_e64 s[6:7], 16, v10
	s_and_b64 s[8:9], s[10:11], s[8:9]
	v_cmp_gt_i32_e64 s[4:5], 0, v10
	s_and_b64 s[6:7], s[8:9], s[6:7]
	s_and_b64 s[4:5], s[6:7], s[4:5]
	v_cndmask_b32_e64 v63, v63, v164, s[38:39]
	v_cndmask_b32_e64 v62, v62, v164, s[36:37]
	v_cndmask_b32_e64 v61, v61, v164, s[34:35]
	v_cndmask_b32_e64 v60, v60, v164, s[30:31]
	v_cndmask_b32_e64 v59, v59, v164, s[28:29]
	v_cndmask_b32_e64 v58, v58, v164, s[26:27]
	v_cndmask_b32_e64 v57, v57, v164, s[24:25]
	v_cndmask_b32_e64 v56, v56, v164, s[22:23]
	v_cndmask_b32_e64 v55, v55, v164, s[20:21]
	v_cndmask_b32_e64 v54, v54, v164, s[18:19]
	v_cndmask_b32_e64 v53, v53, v164, s[16:17]
	v_cndmask_b32_e64 v52, v52, v164, s[14:15]
	v_cndmask_b32_e64 v51, v51, v164, s[10:11]
	v_cndmask_b32_e64 v50, v50, v164, s[8:9]
	v_cndmask_b32_e64 v49, v49, v164, s[6:7]
	v_cndmask_b32_e64 v48, v48, v164, s[4:5]

; #define LAS __attribute__((address_space(3)))
; #define MFMA32(a, b, c) __builtin_amdgcn_mfma_f32_32x32x16_bf16((a), (b), (c), 0, 0, 0)
; template <int MODE>
; DI void nsa_tile(LAS const unsigned char* buf, const bf16x8 (&qf)[4], f32x16 (&o)[2], float& m, float& l, int kbase0, int t, bool lanesel, float slope2, int c, int hi) {
;     ...
;         const int klo = kbase0 + 32 * sub;
;         bool full, none;
;         if (MODE == 0) { full = lanesel && (klo + 31 <= t); none = !lanesel || (klo > t); }
;         else { full = (klo + 31 <= t) && (klo >= t - 511); none = (klo > t) || (klo + 31 < t - 511); }
;         if (__all(none)) continue;
;         int dbase = t - klo - 4 * hi;
;         asm volatile("" : "+v"(dbase));
;         const float b0 = none ? -1e30f : -slope2 * (float)dbase;
;         f32x16 s;
; #pragma unroll
;         for (int i = 0; i < 16; ++i) s[i] = fmaf(slope2, (float)((i & 3) + 8 * (i >> 2)), b0);
; #pragma unroll
;         for (int st = 0; st < 4; ++st) {
;             const bf16x8 a = *(LAS const bf16x8*)(buf + (32 * sub + c) * 144 + st * 32 + hi * 16);
;             s = MFMA32(a, qf[st], s);
;         }
;         if (__any(!full && !none)) {
; #pragma unroll
;             for (int i = 0; i < 16; ++i) {
;                 const int dist = dbase - ((i & 3) + 8 * (i >> 2));
;                 const bool valid = (MODE == 0) ? (lanesel && dist >= 0) : ((unsigned)dist < 512u);
;                 if (!valid) s[i] = -1e30f;
;             }
;         }
.LBB0_822:
	s_ashr_i32 s2, s4, 5
	v_lshl_add_u32 v80, s2, 2, v113
	ds_read_b32 v80, v80
	s_and_b32 s2, s4, 31
	s_waitcnt lgkmcnt(0)
	v_lshrrev_b32_e32 v81, s4, v80
	v_bfe_u32 v80, v80, s2, 1
	v_and_b32_e32 v81, 1, v81
	v_cmp_ne_u32_e32 vcc, 0, v80
	v_cmp_eq_u32_e64 s[2:3], 1, v81
	s_cbranch_vccz .LBB0_835
	s_lshl_b32 s15, s4, 6
	s_xor_b64 s[6:7], s[2:3], -1
	v_cmp_gt_i32_e32 vcc, s15, v150
	s_mul_i32 s5, s11, 0x4600
	s_or_b64 vcc, vcc, s[6:7]
	s_add_i32 s14, s5, 0
	v_add_u32_e32 v80, s14, v0
	s_mov_b64 s[4:5], vcc
	s_cmp_eq_u64 s[4:5], exec
	v_add_u32_e32 v119, v80, v171
	s_cbranch_scc1 .LBB0_829
	v_subrev_u32_e32 v120, s15, v117
	ds_read_b128 v[122:125], v119
	ds_read_b128 v[200:203], v119 offset:32
	ds_read_b128 v[204:207], v119 offset:64
	ds_read_b128 v[208:211], v119 offset:96
	v_cvt_f32_i32_e32 v80, v120
	s_or_b32 s4, s15, 31
	v_cmp_gt_i32_e64 s[4:5], s4, v150
	s_or_b64 s[4:5], s[6:7], s[4:5]
	v_mul_f32_e64 v80, -v152, v80
	v_cndmask_b32_e32 v94, v80, v164, vcc
	v_sub_f32_e32 v94, v94, v248
	v_fma_f32 v80, 0, v152, v94
	v_add_f32_e32 v81, v152, v94
	v_pk_fma_f32 v[82:83], v[152:153], s[72:73], v[94:95] op_sel_hi:[1,1,0]
	v_pk_fma_f32 v[84:85], v[152:153], s[74:75], v[94:95] op_sel_hi:[1,1,0]
	v_pk_fma_f32 v[86:87], v[152:153], s[76:77], v[94:95] op_sel_hi:[1,1,0]
	v_pk_fma_f32 v[88:89], v[152:153], s[70:71], v[94:95] op_sel_hi:[1,1,0]
	v_pk_fma_f32 v[90:91], v[152:153], s[78:79], v[94:95] op_sel_hi:[1,1,0]
	v_pk_fma_f32 v[92:93], v[152:153], s[80:81], v[94:95] op_sel_hi:[1,1,0]
	v_pk_fma_f32 v[94:95], v[152:153], s[82:83], v[94:95] op_sel_hi:[1,1,0]
	s_xor_b64 s[4:5], vcc, s[4:5]
	s_waitcnt lgkmcnt(3)
	v_mfma_f32_32x32x16_bf16 v[80:95], v[122:125], v[128:131], v[80:95]
	s_waitcnt lgkmcnt(2)
	v_mfma_f32_32x32x16_bf16 v[80:95], v[200:203], v[132:135], v[80:95]
	s_waitcnt lgkmcnt(1)
	v_mfma_f32_32x32x16_bf16 v[80:95], v[204:207], v[136:139], v[80:95]
	s_waitcnt lgkmcnt(0)
	v_mfma_f32_32x32x16_bf16 v[80:95], v[208:211], v[140:143], v[80:95]
	s_cmp_lg_u64 s[4:5], 0
	s_cbranch_scc0 .LBB0_826
	v_cmp_lt_i32_e32 vcc, -1, v120
	s_and_b64 vcc, s[2:3], vcc
	s_nop 8
	v_cndmask_b32_e32 v80, v164, v80, vcc
	v_cmp_lt_i32_e32 vcc, 0, v120
	s_and_b64 vcc, s[2:3], vcc
	s_nop 0
	v_cndmask_b32_e32 v81, v164, v81, vcc
	v_cmp_lt_i32_e32 vcc, 1, v120
	s_and_b64 vcc, s[2:3], vcc
	s_nop 0
	v_cndmask_b32_e32 v82, v164, v82, vcc
	v_cmp_lt_i32_e32 vcc, 2, v120
	s_and_b64 vcc, s[2:3], vcc
	s_nop 0
	v_cndmask_b32_e32 v83, v164, v83, vcc
	v_cmp_lt_i32_e32 vcc, 7, v120
	s_and_b64 vcc, s[2:3], vcc
	s_nop 0
	v_cndmask_b32_e32 v84, v164, v84, vcc
	v_cmp_lt_i32_e32 vcc, 8, v120
	s_and_b64 vcc, s[2:3], vcc
	s_nop 0
	v_cndmask_b32_e32 v85, v164, v85, vcc
	v_cmp_lt_i32_e32 vcc, 9, v120
	s_and_b64 vcc, s[2:3], vcc
	s_nop 0
	v_cndmask_b32_e32 v86, v164, v86, vcc
	v_cmp_lt_i32_e32 vcc, 10, v120
	s_and_b64 vcc, s[2:3], vcc
	s_nop 0
	v_cndmask_b32_e32 v87, v164, v87, vcc
	v_cmp_lt_i32_e32 vcc, 15, v120
	s_and_b64 vcc, s[2:3], vcc
	s_nop 0
	v_cndmask_b32_e32 v88, v164, v88, vcc
	v_cmp_lt_i32_e32 vcc, 16, v120
	s_and_b64 vcc, s[2:3], vcc
	s_nop 0
	v_cndmask_b32_e32 v89, v164, v89, vcc
	v_cmp_lt_i32_e32 vcc, 17, v120
	s_and_b64 vcc, s[2:3], vcc
	s_nop 0
	v_cndmask_b32_e32 v90, v164, v90, vcc
	v_cmp_lt_i32_e32 vcc, 18, v120
	s_and_b64 vcc, s[2:3], vcc
	s_nop 0
	v_cndmask_b32_e32 v91, v164, v91, vcc
	v_cmp_lt_i32_e32 vcc, 23, v120
	s_and_b64 vcc, s[2:3], vcc
	s_nop 0
	v_cndmask_b32_e32 v92, v164, v92, vcc
	v_cmp_lt_i32_e32 vcc, 24, v120
	s_and_b64 vcc, s[2:3], vcc
	s_nop 0
	v_cndmask_b32_e32 v93, v164, v93, vcc
	v_cmp_lt_i32_e32 vcc, 25, v120
	s_and_b64 vcc, s[2:3], vcc
	s_nop 0
	v_cndmask_b32_e32 v94, v164, v94, vcc
	v_cmp_lt_i32_e32 vcc, 26, v120
	s_and_b64 vcc, s[2:3], vcc
	s_nop 0
	v_cndmask_b32_e32 v95, v164, v95, vcc

; #define LAS __attribute__((address_space(3)))
; #define MFMA32(a, b, c) __builtin_amdgcn_mfma_f32_32x32x16_bf16((a), (b), (c), 0, 0, 0)
; template <int MODE>
; DI void nsa_tile(LAS const unsigned char* buf, const bf16x8 (&qf)[4], f32x16 (&o)[2], float& m, float& l, int kbase0, int t, bool lanesel, float slope2, int c, int hi) {
;     ...
;         const int klo = kbase0 + 32 * sub;
;         bool full, none;
;         if (MODE == 0) { full = lanesel && (klo + 31 <= t); none = !lanesel || (klo > t); }
;         else { full = (klo + 31 <= t) && (klo >= t - 511); none = (klo > t) || (klo + 31 < t - 511); }
;         if (__all(none)) continue;
;         int dbase = t - klo - 4 * hi;
;         asm volatile("" : "+v"(dbase));
;         const float b0 = none ? -1e30f : -slope2 * (float)dbase;
;         f32x16 s;
; #pragma unroll
;         for (int i = 0; i < 16; ++i) s[i] = fmaf(slope2, (float)((i & 3) + 8 * (i >> 2)), b0);
; #pragma unroll
;         for (int st = 0; st < 4; ++st) {
;             const bf16x8 a = *(LAS const bf16x8*)(buf + (32 * sub + c) * 144 + st * 32 + hi * 16);
;             s = MFMA32(a, qf[st], s);
;         }
;         if (__any(!full && !none)) {
; #pragma unroll
;             for (int i = 0; i < 16; ++i) {
;                 const int dist = dbase - ((i & 3) + 8 * (i >> 2));
;                 const bool valid = (MODE == 0) ? (lanesel && dist >= 0) : ((unsigned)dist < 512u);
;                 if (!valid) s[i] = -1e30f;
;             }
;         }
.LBB0_829:
	s_or_b32 s16, s15, 32
	v_cmp_gt_i32_e32 vcc, s16, v150
	s_or_b64 vcc, s[6:7], vcc
	s_nop 0
	s_mov_b64 s[4:5], vcc
	s_cmp_eq_u64 s[4:5], exec
	s_cbranch_scc1 .LBB0_835
	v_subrev_u32_e32 v120, s16, v117
	ds_read_b128 v[122:125], v119 offset:4608
	ds_read_b128 v[200:203], v119 offset:4640
	ds_read_b128 v[204:207], v119 offset:4672
	ds_read_b128 v[208:211], v119 offset:4704
	v_cvt_f32_i32_e32 v80, v120
	s_or_b32 s4, s15, 63
	v_cmp_gt_i32_e64 s[4:5], s4, v150
	s_xor_b64 s[6:7], vcc, -1
	v_mul_f32_e64 v80, -v152, v80
	v_cndmask_b32_e32 v94, v80, v164, vcc
	v_sub_f32_e32 v94, v94, v248
	v_fma_f32 v80, 0, v152, v94
	v_add_f32_e32 v81, v152, v94
	v_pk_fma_f32 v[82:83], v[152:153], s[72:73], v[94:95] op_sel_hi:[1,1,0]
	v_pk_fma_f32 v[84:85], v[152:153], s[74:75], v[94:95] op_sel_hi:[1,1,0]
	v_pk_fma_f32 v[86:87], v[152:153], s[76:77], v[94:95] op_sel_hi:[1,1,0]
	v_pk_fma_f32 v[88:89], v[152:153], s[70:71], v[94:95] op_sel_hi:[1,1,0]
	v_pk_fma_f32 v[90:91], v[152:153], s[78:79], v[94:95] op_sel_hi:[1,1,0]
	v_pk_fma_f32 v[92:93], v[152:153], s[80:81], v[94:95] op_sel_hi:[1,1,0]
	v_pk_fma_f32 v[94:95], v[152:153], s[82:83], v[94:95] op_sel_hi:[1,1,0]
	s_and_b64 s[4:5], s[6:7], s[4:5]
	s_waitcnt lgkmcnt(3)
	v_mfma_f32_32x32x16_bf16 v[80:95], v[122:125], v[128:131], v[80:95]
	s_waitcnt lgkmcnt(2)
	v_mfma_f32_32x32x16_bf16 v[80:95], v[200:203], v[132:135], v[80:95]
	s_waitcnt lgkmcnt(1)
	v_mfma_f32_32x32x16_bf16 v[80:95], v[204:207], v[136:139], v[80:95]
	s_waitcnt lgkmcnt(0)
	v_mfma_f32_32x32x16_bf16 v[80:95], v[208:211], v[140:143], v[80:95]
	s_cmp_lg_u64 s[4:5], 0
	s_cbranch_scc0 .LBB0_832
	v_cmp_lt_i32_e32 vcc, -1, v120
	s_and_b64 vcc, s[2:3], vcc
	s_nop 8
	v_cndmask_b32_e32 v80, v164, v80, vcc
	v_cmp_lt_i32_e32 vcc, 0, v120
	s_and_b64 vcc, s[2:3], vcc
	s_nop 0
	v_cndmask_b32_e32 v81, v164, v81, vcc
	v_cmp_lt_i32_e32 vcc, 1, v120
	s_and_b64 vcc, s[2:3], vcc
	s_nop 0
	v_cndmask_b32_e32 v82, v164, v82, vcc
	v_cmp_lt_i32_e32 vcc, 2, v120
	s_and_b64 vcc, s[2:3], vcc
	s_nop 0
	v_cndmask_b32_e32 v83, v164, v83, vcc
	v_cmp_lt_i32_e32 vcc, 7, v120
	s_and_b64 vcc, s[2:3], vcc
	s_nop 0
	v_cndmask_b32_e32 v84, v164, v84, vcc
	v_cmp_lt_i32_e32 vcc, 8, v120
	s_and_b64 vcc, s[2:3], vcc
	s_nop 0
	v_cndmask_b32_e32 v85, v164, v85, vcc
	v_cmp_lt_i32_e32 vcc, 9, v120
	s_and_b64 vcc, s[2:3], vcc
	s_nop 0
	v_cndmask_b32_e32 v86, v164, v86, vcc
	v_cmp_lt_i32_e32 vcc, 10, v120
	s_and_b64 vcc, s[2:3], vcc
	s_nop 0
	v_cndmask_b32_e32 v87, v164, v87, vcc
	v_cmp_lt_i32_e32 vcc, 15, v120
	s_and_b64 vcc, s[2:3], vcc
	s_nop 0
	v_cndmask_b32_e32 v88, v164, v88, vcc
	v_cmp_lt_i32_e32 vcc, 16, v120
	s_and_b64 vcc, s[2:3], vcc
	s_nop 0
	v_cndmask_b32_e32 v89, v164, v89, vcc
	v_cmp_lt_i32_e32 vcc, 17, v120
	s_and_b64 vcc, s[2:3], vcc
	s_nop 0
	v_cndmask_b32_e32 v90, v164, v90, vcc
	v_cmp_lt_i32_e32 vcc, 18, v120
	s_and_b64 vcc, s[2:3], vcc
	s_nop 0
	v_cndmask_b32_e32 v91, v164, v91, vcc
	v_cmp_lt_i32_e32 vcc, 23, v120
	s_and_b64 vcc, s[2:3], vcc
	s_nop 0
	v_cndmask_b32_e32 v92, v164, v92, vcc
	v_cmp_lt_i32_e32 vcc, 24, v120
	s_and_b64 vcc, s[2:3], vcc
	s_nop 0
	v_cndmask_b32_e32 v93, v164, v93, vcc
	v_cmp_lt_i32_e32 vcc, 25, v120
	s_and_b64 vcc, s[2:3], vcc
	s_nop 0
	v_cndmask_b32_e32 v94, v164, v94, vcc
	v_cmp_lt_i32_e32 vcc, 26, v120
	s_and_b64 vcc, s[2:3], vcc
	s_nop 0
	v_cndmask_b32_e32 v95, v164, v95, vcc

; #define LAS __attribute__((address_space(3)))
; #define MFMA32(a, b, c) __builtin_amdgcn_mfma_f32_32x32x16_bf16((a), (b), (c), 0, 0, 0)
; template <int MODE>
; DI void nsa_tile(LAS const unsigned char* buf, const bf16x8 (&qf)[4], f32x16 (&o)[2], float& m, float& l, int kbase0, int t, bool lanesel, float slope2, int c, int hi) {
;     ...
;     for (int sub = 0; sub < 2; ++sub) {
;         const int klo = kbase0 + 32 * sub;
;         bool full, none;
;         if (MODE == 0) { full = lanesel && (klo + 31 <= t); none = !lanesel || (klo > t); }
;         else { full = (klo + 31 <= t) && (klo >= t - 511); none = (klo > t) || (klo + 31 < t - 511); }
;         if (__all(none)) continue;
;         int dbase = t - klo - 4 * hi;
;         asm volatile("" : "+v"(dbase));
;         const float b0 = none ? -1e30f : -slope2 * (float)dbase;
;         f32x16 s;
; #pragma unroll
;         for (int i = 0; i < 16; ++i) s[i] = fmaf(slope2, (float)((i & 3) + 8 * (i >> 2)), b0);
; #pragma unroll
;         for (int st = 0; st < 4; ++st) {
;             const bf16x8 a = *(LAS const bf16x8*)(buf + (32 * sub + c) * 144 + st * 32 + hi * 16);
;             s = MFMA32(a, qf[st], s);
;         }
;         if (__any(!full && !none)) {
; #pragma unroll
;             for (int i = 0; i < 16; ++i) {
;                 const int dist = dbase - ((i & 3) + 8 * (i >> 2));
;                 const bool valid = (MODE == 0) ? (lanesel && dist >= 0) : ((unsigned)dist < 512u);
;                 if (!valid) s[i] = -1e30f;
;             }
.LBB0_846:
	s_add_i32 s11, s8, 63
	s_cmp_lt_i32 s11, s40
	s_cselect_b64 s[2:3], -1, 0
	s_cmp_gt_i32 s8, s55
	s_cselect_b64 s[4:5], -1, 0
	s_or_b64 s[2:3], s[4:5], s[2:3]
	s_and_b64 vcc, exec, s[2:3]
	s_cbranch_vccnz .LBB0_859
	s_mul_i32 s2, s9, 0x4600
	s_add_i32 s4, s8, 31
	s_add_i32 s10, s2, 0
	v_cmp_gt_i32_e32 vcc, s8, v150
	v_cmp_lt_i32_e64 s[2:3], s4, v178
	s_or_b64 vcc, vcc, s[2:3]
	v_add_u32_e32 v112, s10, v0
	s_mov_b64 s[2:3], vcc
	s_cmp_eq_u64 s[2:3], exec
	v_add_u32_e32 v181, v112, v171
	s_cbranch_scc1 .LBB0_853
	v_add_u32_e32 v182, 32, v179
	ds_read_b128 v[184:187], v181
	ds_read_b128 v[200:203], v181 offset:32
	ds_read_b128 v[204:207], v181 offset:64
	ds_read_b128 v[208:211], v181 offset:96
	v_cvt_f32_i32_e32 v112, v182
	v_cmp_gt_i32_e64 s[2:3], s4, v150
	v_cmp_lt_i32_e64 s[4:5], s8, v178
	s_or_b64 s[2:3], s[2:3], s[4:5]
	v_mul_f32_e64 v112, -v152, v112
	v_cndmask_b32_e32 v126, v112, v164, vcc
	v_sub_f32_e32 v126, v126, v249
	v_fma_f32 v112, 0, v152, v126
	v_add_f32_e32 v113, v152, v126
	v_pk_fma_f32 v[114:115], v[152:153], s[72:73], v[126:127] op_sel_hi:[1,1,0]
	v_pk_fma_f32 v[116:117], v[152:153], s[74:75], v[126:127] op_sel_hi:[1,1,0]
	v_pk_fma_f32 v[118:119], v[152:153], s[76:77], v[126:127] op_sel_hi:[1,1,0]
	v_pk_fma_f32 v[120:121], v[152:153], s[70:71], v[126:127] op_sel_hi:[1,1,0]
	v_pk_fma_f32 v[122:123], v[152:153], s[78:79], v[126:127] op_sel_hi:[1,1,0]
	v_pk_fma_f32 v[124:125], v[152:153], s[80:81], v[126:127] op_sel_hi:[1,1,0]
	v_pk_fma_f32 v[126:127], v[152:153], s[82:83], v[126:127] op_sel_hi:[1,1,0]
	s_xor_b64 s[4:5], vcc, -1
	s_and_b64 s[2:3], s[2:3], s[4:5]
	s_waitcnt lgkmcnt(3)
	v_mfma_f32_32x32x16_bf16 v[112:127], v[184:187], v[128:131], v[112:127]
	s_waitcnt lgkmcnt(2)
	v_mfma_f32_32x32x16_bf16 v[112:127], v[200:203], v[132:135], v[112:127]
	s_waitcnt lgkmcnt(1)
	v_mfma_f32_32x32x16_bf16 v[112:127], v[204:207], v[136:139], v[112:127]
	s_waitcnt lgkmcnt(0)
	v_mfma_f32_32x32x16_bf16 v[112:127], v[208:211], v[140:143], v[112:127]
	s_cmp_lg_u64 s[2:3], 0
	s_cbranch_scc0 .LBB0_850
	v_cmp_gt_u32_e32 vcc, s89, v182
	v_add_u32_e32 v183, -1, v182
	s_nop 8
	v_cndmask_b32_e32 v112, v164, v112, vcc
	v_cmp_gt_u32_e32 vcc, s89, v183
	v_add_u32_e32 v183, -2, v182
	s_nop 0
	v_cndmask_b32_e32 v113, v164, v113, vcc
	v_cmp_gt_u32_e32 vcc, s89, v183
	v_add_u32_e32 v183, -3, v182
	s_nop 0
	v_cndmask_b32_e32 v114, v164, v114, vcc
	v_cmp_gt_u32_e32 vcc, s89, v183
	v_add_u32_e32 v183, -8, v182
	s_nop 0
	v_cndmask_b32_e32 v115, v164, v115, vcc
	v_cmp_gt_u32_e32 vcc, s89, v183
	v_add_u32_e32 v183, -9, v182
	s_nop 0
	v_cndmask_b32_e32 v116, v164, v116, vcc
	v_cmp_gt_u32_e32 vcc, s89, v183
	v_add_u32_e32 v183, -10, v182
	s_nop 0
	v_cndmask_b32_e32 v117, v164, v117, vcc
	v_cmp_gt_u32_e32 vcc, s89, v183
	v_add_u32_e32 v183, -11, v182
	s_nop 0
	v_cndmask_b32_e32 v118, v164, v118, vcc
	v_cmp_gt_u32_e32 vcc, s89, v183
	v_add_u32_e32 v183, -16, v182
	s_nop 0
	v_cndmask_b32_e32 v119, v164, v119, vcc
	v_cmp_gt_u32_e32 vcc, s89, v183
	v_subrev_u32_e32 v183, 17, v182
	s_nop 0
	v_cndmask_b32_e32 v120, v164, v120, vcc
	v_cmp_gt_u32_e32 vcc, s89, v183
	v_subrev_u32_e32 v183, 18, v182
	s_nop 0
	v_cndmask_b32_e32 v121, v164, v121, vcc
	v_cmp_gt_u32_e32 vcc, s89, v183
	v_subrev_u32_e32 v183, 19, v182
	s_nop 0
	v_cndmask_b32_e32 v122, v164, v122, vcc
	v_cmp_gt_u32_e32 vcc, s89, v183
	v_subrev_u32_e32 v183, 24, v182
	s_nop 0
	v_cndmask_b32_e32 v123, v164, v123, vcc
	v_cmp_gt_u32_e32 vcc, s89, v183
	v_subrev_u32_e32 v183, 25, v182
	s_nop 0
	v_cndmask_b32_e32 v124, v164, v124, vcc
	v_cmp_gt_u32_e32 vcc, s89, v183
	v_subrev_u32_e32 v183, 26, v182
	v_subrev_u32_e32 v182, 27, v182
	v_cndmask_b32_e32 v125, v164, v125, vcc
	v_cmp_gt_u32_e32 vcc, s89, v183
	s_nop 1
	v_cndmask_b32_e32 v126, v164, v126, vcc
	v_cmp_gt_u32_e32 vcc, s89, v182
	s_nop 1
	v_cndmask_b32_e32 v127, v164, v127, vcc

; #define LAS __attribute__((address_space(3)))
; #define MFMA32(a, b, c) __builtin_amdgcn_mfma_f32_32x32x16_bf16((a), (b), (c), 0, 0, 0)
; template <int MODE>
; DI void nsa_tile(LAS const unsigned char* buf, const bf16x8 (&qf)[4], f32x16 (&o)[2], float& m, float& l, int kbase0, int t, bool lanesel, float slope2, int c, int hi) {
;     ...
;     for (int sub = 0; sub < 2; ++sub) {
;         const int klo = kbase0 + 32 * sub;
;         bool full, none;
;         if (MODE == 0) { full = lanesel && (klo + 31 <= t); none = !lanesel || (klo > t); }
;         else { full = (klo + 31 <= t) && (klo >= t - 511); none = (klo > t) || (klo + 31 < t - 511); }
;         if (__all(none)) continue;
;         int dbase = t - klo - 4 * hi;
;         asm volatile("" : "+v"(dbase));
;         const float b0 = none ? -1e30f : -slope2 * (float)dbase;
;         f32x16 s;
; #pragma unroll
;         for (int i = 0; i < 16; ++i) s[i] = fmaf(slope2, (float)((i & 3) + 8 * (i >> 2)), b0);
; #pragma unroll
;         for (int st = 0; st < 4; ++st) {
;             const bf16x8 a = *(LAS const bf16x8*)(buf + (32 * sub + c) * 144 + st * 32 + hi * 16);
;             s = MFMA32(a, qf[st], s);
;         }
;         if (__any(!full && !none)) {
; #pragma unroll
;             for (int i = 0; i < 16; ++i) {
;                 const int dist = dbase - ((i & 3) + 8 * (i >> 2));
;                 const bool valid = (MODE == 0) ? (lanesel && dist >= 0) : ((unsigned)dist < 512u);
;                 if (!valid) s[i] = -1e30f;
;             }
.LBB0_853:
	s_add_i32 s4, s8, 32
	v_cmp_gt_i32_e32 vcc, s4, v150
	v_cmp_lt_i32_e64 s[2:3], s11, v178
	s_or_b64 vcc, vcc, s[2:3]
	s_mov_b64 s[2:3], vcc
	s_cmp_eq_u64 s[2:3], exec
	s_cbranch_scc1 .LBB0_859
	v_mov_b32_e32 v182, v179
	ds_read_b128 v[184:187], v181 offset:4608
	ds_read_b128 v[200:203], v181 offset:4640
	ds_read_b128 v[204:207], v181 offset:4672
	ds_read_b128 v[208:211], v181 offset:4704
	v_cvt_f32_i32_e32 v112, v182
	v_cmp_gt_i32_e64 s[2:3], s11, v150
	v_cmp_lt_i32_e64 s[4:5], s4, v178
	s_or_b64 s[2:3], s[2:3], s[4:5]
	v_mul_f32_e64 v112, -v152, v112
	v_cndmask_b32_e32 v126, v112, v164, vcc
	v_sub_f32_e32 v126, v126, v249
	v_fma_f32 v112, 0, v152, v126
	v_add_f32_e32 v113, v152, v126
	v_pk_fma_f32 v[114:115], v[152:153], s[72:73], v[126:127] op_sel_hi:[1,1,0]
	v_pk_fma_f32 v[116:117], v[152:153], s[74:75], v[126:127] op_sel_hi:[1,1,0]
	v_pk_fma_f32 v[118:119], v[152:153], s[76:77], v[126:127] op_sel_hi:[1,1,0]
	v_pk_fma_f32 v[120:121], v[152:153], s[70:71], v[126:127] op_sel_hi:[1,1,0]
	v_pk_fma_f32 v[122:123], v[152:153], s[78:79], v[126:127] op_sel_hi:[1,1,0]
	v_pk_fma_f32 v[124:125], v[152:153], s[80:81], v[126:127] op_sel_hi:[1,1,0]
	v_pk_fma_f32 v[126:127], v[152:153], s[82:83], v[126:127] op_sel_hi:[1,1,0]
	s_xor_b64 s[4:5], vcc, -1
	s_and_b64 s[2:3], s[2:3], s[4:5]
	s_waitcnt lgkmcnt(3)
	v_mfma_f32_32x32x16_bf16 v[112:127], v[184:187], v[128:131], v[112:127]
	s_waitcnt lgkmcnt(2)
	v_mfma_f32_32x32x16_bf16 v[112:127], v[200:203], v[132:135], v[112:127]
	s_waitcnt lgkmcnt(1)
	v_mfma_f32_32x32x16_bf16 v[112:127], v[204:207], v[136:139], v[112:127]
	s_waitcnt lgkmcnt(0)
	v_mfma_f32_32x32x16_bf16 v[112:127], v[208:211], v[140:143], v[112:127]
	s_cmp_lg_u64 s[2:3], 0
	s_cbranch_scc0 .LBB0_856
	v_cmp_gt_u32_e32 vcc, s89, v182
	v_add_u32_e32 v181, -1, v182
	s_nop 8
	v_cndmask_b32_e32 v112, v164, v112, vcc
	v_cmp_gt_u32_e32 vcc, s89, v181
	v_add_u32_e32 v181, -2, v182
	s_nop 0
	v_cndmask_b32_e32 v113, v164, v113, vcc
	v_cmp_gt_u32_e32 vcc, s89, v181
	v_add_u32_e32 v181, -3, v182
	s_nop 0
	v_cndmask_b32_e32 v114, v164, v114, vcc
	v_cmp_gt_u32_e32 vcc, s89, v181
	v_add_u32_e32 v181, -8, v182
	s_nop 0
	v_cndmask_b32_e32 v115, v164, v115, vcc
	v_cmp_gt_u32_e32 vcc, s89, v181
	v_add_u32_e32 v181, -9, v182
	s_nop 0
	v_cndmask_b32_e32 v116, v164, v116, vcc
	v_cmp_gt_u32_e32 vcc, s89, v181
	v_add_u32_e32 v181, -10, v182
	s_nop 0
	v_cndmask_b32_e32 v117, v164, v117, vcc
	v_cmp_gt_u32_e32 vcc, s89, v181
	v_add_u32_e32 v181, -11, v182
	s_nop 0
	v_cndmask_b32_e32 v118, v164, v118, vcc
	v_cmp_gt_u32_e32 vcc, s89, v181
	v_add_u32_e32 v181, -16, v182
	s_nop 0
	v_cndmask_b32_e32 v119, v164, v119, vcc
	v_cmp_gt_u32_e32 vcc, s89, v181
	v_subrev_u32_e32 v181, 17, v182
	s_nop 0
	v_cndmask_b32_e32 v120, v164, v120, vcc
	v_cmp_gt_u32_e32 vcc, s89, v181
	v_subrev_u32_e32 v181, 18, v182
	s_nop 0
	v_cndmask_b32_e32 v121, v164, v121, vcc
	v_cmp_gt_u32_e32 vcc, s89, v181
	v_subrev_u32_e32 v181, 19, v182
	s_nop 0
	v_cndmask_b32_e32 v122, v164, v122, vcc
	v_cmp_gt_u32_e32 vcc, s89, v181
	v_subrev_u32_e32 v181, 24, v182
	s_nop 0
	v_cndmask_b32_e32 v123, v164, v123, vcc
	v_cmp_gt_u32_e32 vcc, s89, v181
	v_subrev_u32_e32 v181, 25, v182
	s_nop 0
	v_cndmask_b32_e32 v124, v164, v124, vcc
	v_cmp_gt_u32_e32 vcc, s89, v181
	v_subrev_u32_e32 v181, 26, v182
	s_nop 0
	v_cndmask_b32_e32 v125, v164, v125, vcc
	v_cmp_gt_u32_e32 vcc, s89, v181
	v_subrev_u32_e32 v181, 27, v182
	s_nop 0
	v_cndmask_b32_e32 v126, v164, v126, vcc
	v_cmp_gt_u32_e32 vcc, s89, v181
	s_nop 1
	v_cndmask_b32_e32 v127, v164, v127, vcc
